# k20 + attn_pv: attention P*V software-pipelined (next step's P conversion and transposed V reads issued before the current step's MFMAs, alternate register set, lgkmcnt recounted)
# baseline (speedup 1.0000x reference)
; __device__ void phase_attn(const Params& p, unsigned char* smem, int wave) {
;     ...
;         const bf16x8 qf0 = *(const bf16x8*)(Qs + (16 * w4 + ql) * ATT_LD + gq * 8), qf1 = *(const bf16x8*)(Qs + (16 * w4 + ql) * ATT_LD + 32 + gq * 8);
;         f32x4 sc[10];
; #pragma unroll
;         for (int kt = 0; kt < 9; ++kt) { const bf16_t* kr = Ks + (16 * w4 + 16 * kt + ql) * ATT_LD + gq * 8;
;             f32x4 a = (f32x4){0.f, 0.f, 0.f, 0.f};
;             a = __builtin_amdgcn_mfma_f32_16x16x32_bf16(*(const bf16x8*)kr, qf0, a, 0, 0, 0);
;             a = __builtin_amdgcn_mfma_f32_16x16x32_bf16(*(const bf16x8*)(kr + 32), qf1, a, 0, 0, 0);
;             sc[kt] = a; if (kt % 3 == 2) __builtin_amdgcn_sched_barrier(0); }
;         const float slope = exp2f(-(float)(h + 1)) * (float)d * 1.4426950408889634f;
;         const int qi = i0 + 16 * w4 + ql;
;         float mx = -1e30f;
; #pragma unroll
;         for (int kt = 0; kt < 9; ++kt)
; #pragma unroll
;             for (int j = 0; j < 4; ++j) { const int rel = 16 * kt + 4 * gq + j - 64 - ql; const int jk = qi + rel;
;                 const bool relok = (kt == 0) ? (rel >= -64) : ((kt == 8) ? (rel <= 64) : true);
;                 const bool ok = relok && ((unsigned)jk < (unsigned)Ls);
;                 const float v = ok ? sc[kt][j] * 0.18033688011112042f - slope * fabsf((float)rel) : -1e30f;
;                 sc[kt][j] = v; mx = fmaxf(mx, v); }
.LBB0_732:
	ds_read_b128 v[46:49], v140 offset:18432
	ds_read_b128 v[186:189], v140
	ds_read_b128 v[50:53], v140 offset:18496
	ds_read_b128 v[190:193], v140 offset:64
	ds_read_b128 v[54:57], v140 offset:20736
	ds_read_b128 v[58:61], v140 offset:20800
	v_readlane_b32 s28, v253, 8
	v_readlane_b32 s30, v253, 10
	v_readlane_b32 s31, v253, 11
	s_add_u32 s59, s30, s20
	s_mul_i32 s18, s22, 0xfffffd80
	s_waitcnt lgkmcnt(4)
	v_mfma_f32_16x16x32_bf16 v[46:49], v[46:49], v[186:189], 0
	s_mul_i32 s19, s22, 0xfffec000
	s_addc_u32 s60, s31, s21
	s_add_i32 s18, s23, s18
	s_waitcnt lgkmcnt(2)
	v_mfma_f32_16x16x32_bf16 v[194:197], v[50:53], v[190:193], v[46:49]
	s_add_i32 s19, s48, s19
	s_and_b32 s57, s22, 7
	s_and_b32 s19, s19, 0xfffff800
	ds_read_b128 v[46:49], v140 offset:23040
	s_waitcnt lgkmcnt(2)
	v_mfma_f32_16x16x32_bf16 v[50:53], v[54:57], v[186:189], 0
	ds_read_b128 v[54:57], v140 offset:23104
	s_and_b32 s20, s18, 15
	s_add_i32 s21, s18, 0xfffffe00
	s_cmpk_lt_i32 s18, 0x200
	s_cselect_b32 s18, s20, s21
	s_cselect_b32 s20, s50, 0x4000
	s_cselect_b32 s61, s19, 0x10000
	s_cmp_eq_u32 s42, 1
	s_cselect_b32 s19, 4, 16
	s_cselect_b32 s21, 2, 4
	s_cmp_lt_u32 s22, 8
	s_waitcnt lgkmcnt(1)
	v_mfma_f32_16x16x32_bf16 v[46:49], v[46:49], v[186:189], 0
	s_cselect_b32 s22, 1, s19
	s_cselect_b32 s58, 0, s21
	s_add_i32 s19, s22, -1
	s_lshr_b32 s63, s20, s58
	s_and_b32 s62, s19, s18
	s_lshr_b32 s20, s18, s58
	v_readlane_b32 s29, v253, 9
	v_mfma_f32_16x16x32_bf16 v[198:201], v[58:61], v[190:193], v[50:53]
	s_waitcnt lgkmcnt(0)
	v_mfma_f32_16x16x32_bf16 v[202:205], v[54:57], v[190:193], v[46:49]
	s_nop 2
	ds_read_b128 v[46:49], v140 offset:25344
	ds_read_b128 v[50:53], v140 offset:25408
	ds_read_b128 v[54:57], v140 offset:27648
	ds_read_b128 v[58:61], v140 offset:27712
	s_waitcnt lgkmcnt(3)
	v_mfma_f32_16x16x32_bf16 v[46:49], v[46:49], v[186:189], 0
	s_waitcnt lgkmcnt(2)
	v_mfma_f32_16x16x32_bf16 v[206:209], v[50:53], v[190:193], v[46:49]
	ds_read_b128 v[50:53], v140 offset:30016
	s_nop 4
	ds_read_b128 v[46:49], v140 offset:29952
	s_waitcnt lgkmcnt(3)
	v_mfma_f32_16x16x32_bf16 v[54:57], v[54:57], v[186:189], 0
	s_waitcnt lgkmcnt(0)
	v_mfma_f32_16x16x32_bf16 v[46:49], v[46:49], v[186:189], 0
	v_mfma_f32_16x16x32_bf16 v[62:65], v[58:61], v[190:193], v[54:57]
	v_mfma_f32_16x16x32_bf16 v[58:61], v[50:53], v[190:193], v[46:49]
	s_nop 5
	ds_read_b128 v[46:49], v140 offset:32256
	ds_read_b128 v[50:53], v140 offset:32320
	ds_read_b128 v[54:57], v140 offset:34560
	ds_read_b128 v[210:213], v140 offset:34624
	s_waitcnt lgkmcnt(3)
	v_mfma_f32_16x16x32_bf16 v[46:49], v[46:49], v[186:189], 0
	s_waitcnt lgkmcnt(1)
	v_mfma_f32_16x16x32_bf16 v[214:217], v[54:57], v[186:189], 0
	v_mfma_f32_16x16x32_bf16 v[54:57], v[50:53], v[190:193], v[46:49]
	s_nop 4
	ds_read_b128 v[46:49], v140 offset:36864
	s_waitcnt lgkmcnt(1)
	v_mfma_f32_16x16x32_bf16 v[50:53], v[210:213], v[190:193], v[214:217]
	ds_read_b128 v[210:213], v140 offset:36928
	s_waitcnt lgkmcnt(1)
	v_mfma_f32_16x16x32_bf16 v[46:49], v[46:49], v[186:189], 0
	s_waitcnt lgkmcnt(0)
	v_mfma_f32_16x16x32_bf16 v[46:49], v[210:213], v[190:193], v[46:49]
	s_add_i32 s18, s57, 1
	v_cvt_f32_ubyte0_e32 v12, s18
	v_cmp_lt_f32_e32 vcc, s51, v12
	s_and_b64 s[18:19], vcc, exec
	s_cselect_b32 s18, 0xffffffc0, 0
	v_cndmask_b32_e32 v13, 0, v181, vcc
	v_sub_f32_e32 v12, v13, v12
	v_exp_f32_e32 v12, v12
	v_lshl_add_u32 v139, s20, 7, v67
	v_cvt_f32_ubyte0_e32 v13, s22
	v_or_b32_e32 v45, v139, v66
	v_ldexp_f32 v12, v12, s18
	v_mul_f32_e32 v13, v12, v13
	v_add_u32_e32 v12, v45, v143
	v_cmp_gt_u32_e64 s[26:27], s63, v12
	v_add_u32_e32 v12, v45, v144
	v_cmp_gt_u32_e64 s[28:29], s63, v12
	v_add_u32_e32 v12, v45, v145
	v_cmp_gt_u32_e64 s[30:31], s63, v12
	v_add_u32_e32 v12, v45, v146
	v_cmp_gt_u32_e64 s[34:35], s63, v12
	v_add_u32_e32 v12, v45, v174
	v_cmp_gt_u32_e64 s[22:23], s63, v12
	v_add_u32_e32 v12, v45, v175
	v_cmp_gt_u32_e64 s[20:21], s63, v12
	v_add_u32_e32 v12, v45, v176
	v_cmp_gt_u32_e32 vcc, s63, v12
	v_add_u32_e32 v12, v45, v177
	v_cmp_gt_u32_e64 s[18:19], s63, v12
	v_mov_b32_e32 v12, v49
	v_pk_mul_f32 v[12:13], v[12:13], s[44:45]
	v_mov_b32_e32 v186, v194
	v_mov_b32_e32 v187, v13
	v_pk_mul_f32 v[186:187], v[68:69], v[186:187]
	s_and_b64 s[26:27], s[24:25], s[26:27]
	v_sub_f32_e32 v49, v186, v187
	v_mov_b32_e32 v186, v195
	v_mov_b32_e32 v187, v13
	v_pk_mul_f32 v[186:187], v[70:71], v[186:187]
	v_cndmask_b32_e64 v194, v182, v49, s[26:27]
	v_sub_f32_e32 v49, v186, v187
	v_mov_b32_e32 v186, v196
	v_mov_b32_e32 v187, v13
	s_and_b64 s[26:27], s[4:5], s[28:29]
	v_pk_mul_f32 v[186:187], v[72:73], v[186:187]
	v_cndmask_b32_e64 v195, v182, v49, s[26:27]
	v_sub_f32_e32 v186, v186, v187
	s_and_b64 s[26:27], s[6:7], s[30:31]
	v_cndmask_b32_e64 v196, v182, v186, s[26:27]
	v_mov_b32_e32 v186, v197
	v_mov_b32_e32 v187, v13
	v_pk_mul_f32 v[186:187], v[74:75], v[186:187]
	s_and_b64 s[26:27], s[8:9], s[34:35]
	v_sub_f32_e32 v186, v186, v187
	v_cndmask_b32_e64 v197, v182, v186, s[26:27]
	v_mov_b32_e32 v186, v198
	v_mov_b32_e32 v187, v13
	v_add_u32_e32 v14, v45, v147
	v_pk_mul_f32 v[186:187], v[76:77], v[186:187]
	v_cmp_gt_u32_e64 s[26:27], s63, v14
	v_sub_f32_e32 v186, v186, v187
	v_mov_b32_e32 v187, v13
	v_cndmask_b32_e64 v14, v182, v186, s[26:27]
	v_mov_b32_e32 v186, v199
	v_add_u32_e32 v188, v45, v148
	v_pk_mul_f32 v[186:187], v[78:79], v[186:187]
	v_cmp_gt_u32_e64 s[26:27], s63, v188
	v_sub_f32_e32 v186, v186, v187
	v_mov_b32_e32 v187, v13
	v_cndmask_b32_e64 v188, v182, v186, s[26:27]
	v_mov_b32_e32 v186, v200
	v_add_u32_e32 v189, v45, v149
	v_pk_mul_f32 v[186:187], v[80:81], v[186:187]
	v_cmp_gt_u32_e64 s[26:27], s63, v189
	v_sub_f32_e32 v186, v186, v187
; __device__ void phase_attn(const Params& p, unsigned char* smem, int wave) {
;     ...
;         for (int kt = 0; kt < 9; ++kt)
; #pragma unroll
;             for (int j = 0; j < 4; ++j) { const int rel = 16 * kt + 4 * gq + j - 64 - ql; const int jk = qi + rel;
;                 const bool relok = (kt == 0) ? (rel >= -64) : ((kt == 8) ? (rel <= 64) : true);
;                 const bool ok = relok && ((unsigned)jk < (unsigned)Ls);
;                 const float v = ok ? sc[kt][j] * 0.18033688011112042f - slope * fabsf((float)rel) : -1e30f;
;                 sc[kt][j] = v; mx = fmaxf(mx, v); }
	v_mov_b32_e32 v187, v13
	v_cndmask_b32_e64 v189, v182, v186, s[26:27]
	v_mov_b32_e32 v186, v201
	v_add_u32_e32 v190, v45, v150
	v_pk_mul_f32 v[186:187], v[82:83], v[186:187]
	v_cmp_gt_u32_e64 s[26:27], s63, v190
	v_sub_f32_e32 v186, v186, v187
	v_mov_b32_e32 v187, v13
	v_cndmask_b32_e64 v190, v182, v186, s[26:27]
	v_mov_b32_e32 v186, v202
	v_add_u32_e32 v191, v45, v151
	v_pk_mul_f32 v[186:187], v[84:85], v[186:187]
	v_cmp_gt_u32_e64 s[26:27], s63, v191
	v_sub_f32_e32 v186, v186, v187
	v_mov_b32_e32 v187, v13
	v_cndmask_b32_e64 v191, v182, v186, s[26:27]
	v_mov_b32_e32 v186, v203
	v_add_u32_e32 v192, v45, v152
	v_pk_mul_f32 v[186:187], v[86:87], v[186:187]
	v_cmp_gt_u32_e64 s[26:27], s63, v192
	v_sub_f32_e32 v186, v186, v187
	v_mov_b32_e32 v187, v13
	v_cndmask_b32_e64 v192, v182, v186, s[26:27]
	v_mov_b32_e32 v186, v204
	v_add_u32_e32 v193, v45, v153
	v_pk_mul_f32 v[186:187], v[88:89], v[186:187]
	v_cmp_gt_u32_e64 s[26:27], s63, v193
	v_sub_f32_e32 v186, v186, v187
	v_mov_b32_e32 v187, v13
	v_cndmask_b32_e64 v193, v182, v186, s[26:27]
	v_mov_b32_e32 v186, v205
	v_add_u32_e32 v210, v45, v154
	v_pk_mul_f32 v[186:187], v[90:91], v[186:187]
	v_cmp_gt_u32_e64 s[26:27], s63, v210
	v_sub_f32_e32 v186, v186, v187
	v_mov_b32_e32 v187, v13
	v_cndmask_b32_e64 v198, v182, v186, s[26:27]
	v_mov_b32_e32 v186, v206
	v_add_u32_e32 v211, v45, v155
	v_pk_mul_f32 v[186:187], v[92:93], v[186:187]
	v_cmp_gt_u32_e64 s[26:27], s63, v211
	v_sub_f32_e32 v186, v186, v187
	v_mov_b32_e32 v187, v13
	v_cndmask_b32_e64 v199, v182, v186, s[26:27]
	v_mov_b32_e32 v186, v207
	v_add_u32_e32 v212, v45, v156
	v_pk_mul_f32 v[186:187], v[94:95], v[186:187]
	v_cmp_gt_u32_e64 s[26:27], s63, v212
	v_sub_f32_e32 v186, v186, v187
	v_mov_b32_e32 v187, v13
	v_cndmask_b32_e64 v200, v182, v186, s[26:27]
	v_mov_b32_e32 v186, v208
	v_add_u32_e32 v213, v45, v157
	v_pk_mul_f32 v[186:187], v[96:97], v[186:187]
	v_cmp_gt_u32_e64 s[26:27], s63, v213
	v_sub_f32_e32 v186, v186, v187
	v_mov_b32_e32 v187, v13
	v_cndmask_b32_e64 v201, v182, v186, s[26:27]
	v_mov_b32_e32 v186, v209
	v_add_u32_e32 v214, v45, v158
	v_pk_mul_f32 v[186:187], v[98:99], v[186:187]
	v_cmp_gt_u32_e64 s[26:27], s63, v214
	v_sub_f32_e32 v186, v186, v187
	v_mov_b32_e32 v187, v13
	v_cndmask_b32_e64 v202, v182, v186, s[26:27]
	v_mov_b32_e32 v186, v62
	v_add_u32_e32 v215, v45, v142
	v_pk_mul_f32 v[186:187], v[100:101], v[186:187]
	v_cmp_gt_u32_e64 s[26:27], s63, v215
	v_sub_f32_e32 v62, v186, v187
	v_add_u32_e32 v216, v45, v159
	v_cndmask_b32_e64 v186, v182, v62, s[26:27]
	v_mov_b32_e32 v62, v63
	v_mov_b32_e32 v63, v13
	v_pk_mul_f32 v[62:63], v[102:103], v[62:63]
	v_cmp_gt_u32_e64 s[26:27], s63, v216
	v_sub_f32_e32 v62, v62, v63
	v_mov_b32_e32 v63, v13
	v_cndmask_b32_e64 v187, v182, v62, s[26:27]
	v_mov_b32_e32 v62, v64
	v_add_u32_e32 v217, v45, v160
	v_pk_mul_f32 v[62:63], v[104:105], v[62:63]
	v_cmp_gt_u32_e64 s[26:27], s63, v217
	v_sub_f32_e32 v62, v62, v63
	v_mov_b32_e32 v63, v13
	v_cndmask_b32_e64 v64, v182, v62, s[26:27]
	v_mov_b32_e32 v62, v65
	v_add_u32_e32 v218, v45, v161
	v_pk_mul_f32 v[62:63], v[106:107], v[62:63]
	v_cmp_gt_u32_e64 s[26:27], s63, v218
	v_sub_f32_e32 v62, v62, v63
	v_mov_b32_e32 v63, v13
	v_cndmask_b32_e64 v65, v182, v62, s[26:27]
	v_mov_b32_e32 v62, v58
	v_add_u32_e32 v219, v45, v162
	v_pk_mul_f32 v[62:63], v[62:63], v[108:109]
	v_cmp_gt_u32_e64 s[26:27], s63, v219
	v_sub_f32_e32 v58, v62, v63
	v_add_u32_e32 v220, v45, v163
	v_cndmask_b32_e64 v62, v182, v58, s[26:27]
	v_mov_b32_e32 v58, v59
	v_mov_b32_e32 v59, v13
	v_pk_mul_f32 v[58:59], v[58:59], v[110:111]
	v_cmp_gt_u32_e64 s[26:27], s63, v220
	v_sub_f32_e32 v58, v58, v59
	v_mov_b32_e32 v59, v13
	v_cndmask_b32_e64 v63, v182, v58, s[26:27]
	v_mov_b32_e32 v58, v60
	v_add_u32_e32 v221, v45, v164
	v_pk_mul_f32 v[58:59], v[58:59], v[112:113]
	v_cmp_gt_u32_e64 s[26:27], s63, v221
	v_sub_f32_e32 v58, v58, v59
	v_mov_b32_e32 v59, v13
	v_cndmask_b32_e64 v60, v182, v58, s[26:27]
	v_mov_b32_e32 v58, v61
	v_add_u32_e32 v222, v45, v165
	v_pk_mul_f32 v[58:59], v[58:59], v[114:115]
	v_cmp_gt_u32_e64 s[26:27], s63, v222
	v_sub_f32_e32 v58, v58, v59
	v_mov_b32_e32 v59, v13
	v_cndmask_b32_e64 v61, v182, v58, s[26:27]
	v_mov_b32_e32 v58, v54
	v_add_u32_e32 v223, v45, v166
	v_pk_mul_f32 v[58:59], v[58:59], v[116:117]
	v_cmp_gt_u32_e64 s[26:27], s63, v223
	v_sub_f32_e32 v54, v58, v59
	v_add_u32_e32 v224, v45, v167
	v_cndmask_b32_e64 v58, v182, v54, s[26:27]
	v_mov_b32_e32 v54, v55
	v_mov_b32_e32 v55, v13
	v_pk_mul_f32 v[54:55], v[54:55], v[118:119]
	v_cmp_gt_u32_e64 s[26:27], s63, v224
	v_sub_f32_e32 v54, v54, v55
	v_mov_b32_e32 v55, v13
	v_cndmask_b32_e64 v59, v182, v54, s[26:27]
	v_mov_b32_e32 v54, v56
	v_add_u32_e32 v225, v45, v168
	v_pk_mul_f32 v[54:55], v[54:55], v[120:121]
	v_cmp_gt_u32_e64 s[26:27], s63, v225
	v_sub_f32_e32 v54, v54, v55
	v_mov_b32_e32 v55, v13
	v_cndmask_b32_e64 v56, v182, v54, s[26:27]
	v_mov_b32_e32 v54, v57
	v_add_u32_e32 v226, v45, v169
	v_pk_mul_f32 v[54:55], v[54:55], v[122:123]
	v_cmp_gt_u32_e64 s[26:27], s63, v226
	v_sub_f32_e32 v54, v54, v55
	v_mov_b32_e32 v55, v13
	v_cndmask_b32_e64 v57, v182, v54, s[26:27]
	v_mov_b32_e32 v54, v50
	v_add_u32_e32 v227, v45, v170
	v_pk_mul_f32 v[54:55], v[54:55], v[124:125]
	v_cmp_gt_u32_e64 s[26:27], s63, v227
	v_sub_f32_e32 v50, v54, v55
	v_max3_f32 v49, v194, s52, v195
	v_cndmask_b32_e64 v54, v182, v50, s[26:27]
	v_mov_b32_e32 v50, v51
	v_mov_b32_e32 v51, v13
	v_add_u32_e32 v228, v45, v171
	v_max3_f32 v49, v49, v196, v197
	v_pk_mul_f32 v[50:51], v[50:51], v[126:127]
	v_max3_f32 v49, v49, v14, v188
	v_sub_f32_e32 v50, v50, v51
	v_cmp_gt_u32_e64 s[26:27], s63, v228
	v_max3_f32 v49, v49, v189, v190
; __device__ __forceinline__ unsigned cvtpk(float lo, float hi) { const f32v2_t v = {lo, hi}; const bf16v2_t b = __builtin_convertvector(v, bf16v2_t); return __builtin_bit_cast(unsigned, b); }
; __device__ __forceinline__ v4i16_t lds_tr16(const bf16_t* p) { return __builtin_amdgcn_ds_read_tr16_b64_v4i16((LAS v4i16_t*)p); }
; __device__ void phase_attn(const Params& p, unsigned char* smem, int wave) {
;     ...
;         mx = fmaxf(mx, __shfl_xor(mx, 16)); mx = fmaxf(mx, __shfl_xor(mx, 32));
;         float den = 0.f;
; #pragma unroll
;         for (int kt = 0; kt < 9; ++kt)
; #pragma unroll
;             for (int j = 0; j < 4; ++j) { const float pv = __builtin_amdgcn_exp2f(sc[kt][j] - mx); sc[kt][j] = pv; den += pv; }
;         sc[9] = (f32x4){0.f, 0.f, 0.f, 0.f};
;         den += __shfl_xor(den, 16); den += __shfl_xor(den, 32);
;         f32x4 oacc[4];
; #pragma unroll
;         for (int et = 0; et < 4; ++et) oacc[et] = (f32x4){0.f, 0.f, 0.f, 0.f};
; #pragma unroll
;         for (int ks = 0; ks < 5; ++ks) {
;             u32x4 pu; pu.x = cvtpk(sc[2 * ks][0], sc[2 * ks][1]); pu.y = cvtpk(sc[2 * ks][2], sc[2 * ks][3]); pu.z = cvtpk(sc[2 * ks + 1][0], sc[2 * ks + 1][1]); pu.w = cvtpk(sc[2 * ks + 1][2], sc[2 * ks + 1][3]);
;             const bf16x8 pf = __builtin_bit_cast(bf16x8, pu);
;             const bf16_t* vrow = Vs + (16 * w4 + 32 * ks + 4 * gq + (ql >> 2)) * ATT_LD + 4 * (ql & 3);
; #pragma unroll
;             for (int et = 0; et < 4; ++et) {
;                 const v4i16_t t0 = lds_tr16(vrow + 16 * et);
;                 v4i16_t t1 = (v4i16_t){0, 0, 0, 0};
;                 if (ks < 4) t1 = lds_tr16(vrow + 16 * ATT_LD + 16 * et);
;                 const bf16x8 vf = __builtin_shufflevector(t0, t1, 0, 1, 2, 3, 4, 5, 6, 7);
;                 oacc[et] = __builtin_amdgcn_mfma_f32_16x16x32_bf16(pf, vf, oacc[et], 0, 0, 0); }
	v_mov_b32_e32 v51, v13
	v_cndmask_b32_e64 v55, v182, v50, s[26:27]
	v_mov_b32_e32 v50, v52
	v_add_u32_e32 v229, v45, v172
	v_max3_f32 v49, v49, v191, v192
	v_pk_mul_f32 v[50:51], v[50:51], v[128:129]
	v_max3_f32 v49, v49, v193, v198
	v_sub_f32_e32 v50, v50, v51
	v_cmp_gt_u32_e64 s[26:27], s63, v229
	v_max3_f32 v49, v49, v199, v200
	v_mov_b32_e32 v51, v13
	v_cndmask_b32_e64 v52, v182, v50, s[26:27]
	v_mov_b32_e32 v50, v53
	v_add_u32_e32 v230, v45, v173
	v_max3_f32 v49, v49, v201, v202
	v_pk_mul_f32 v[50:51], v[50:51], v[130:131]
	v_max3_f32 v49, v49, v186, v187
	v_sub_f32_e32 v50, v50, v51
	v_cmp_gt_u32_e64 s[26:27], s63, v230
	v_max3_f32 v49, v49, v64, v65
	v_mov_b32_e32 v51, v13
	v_cndmask_b32_e64 v53, v182, v50, s[26:27]
	v_mov_b32_e32 v50, v46
	v_max3_f32 v49, v49, v62, v63
	v_pk_mul_f32 v[50:51], v[50:51], v[132:133]
	v_max3_f32 v49, v49, v60, v61
	v_sub_f32_e32 v46, v50, v51
	s_and_b64 s[22:23], s[10:11], s[22:23]
	v_max3_f32 v49, v49, v58, v59
	v_cndmask_b32_e64 v50, v182, v46, s[22:23]
	v_mov_b32_e32 v46, v47
	v_mov_b32_e32 v47, v13
	v_max3_f32 v49, v49, v56, v57
	v_pk_mul_f32 v[46:47], v[46:47], v[134:135]
	v_max3_f32 v49, v49, v54, v55
	v_sub_f32_e32 v46, v46, v47
	s_and_b64 s[20:21], s[12:13], s[20:21]
	v_max3_f32 v49, v49, v52, v53
	v_cndmask_b32_e64 v51, v182, v46, s[20:21]
	v_max3_f32 v203, v49, v50, v51
	v_mov_b32_e32 v49, v13
	v_pk_mul_f32 v[46:47], v[48:49], v[136:137]
	s_and_b64 vcc, s[14:15], vcc
	v_sub_f32_e32 v46, v46, v47
	v_and_b32_e32 v206, 64, v183
	v_cndmask_b32_e32 v47, v182, v46, vcc
	v_fma_f32 v12, -v13, v178, v12
	s_and_b64 vcc, s[16:17], s[18:19]
	v_xor_b32_e32 v46, 16, v183
	v_add_u32_e32 v48, 64, v206
	v_cndmask_b32_e32 v12, v182, v12, vcc
	v_cmp_lt_i32_e32 vcc, v46, v48
	v_max3_f32 v13, v203, v47, v12
	s_nop 0
	v_cndmask_b32_e32 v46, v183, v46, vcc
	v_lshlrev_b32_e32 v203, 2, v46
	ds_bpermute_b32 v46, v203, v13
	s_waitcnt lgkmcnt(0)
	v_max_f32_e32 v46, v46, v46
	v_max_f32_e32 v13, v13, v46
	v_xor_b32_e32 v46, 32, v183
	v_cmp_lt_i32_e32 vcc, v46, v48
	s_nop 1
	v_cndmask_b32_e32 v46, v183, v46, vcc
	v_lshlrev_b32_e32 v204, 2, v46
	ds_bpermute_b32 v46, v204, v13
	s_waitcnt lgkmcnt(0)
	v_max_f32_e32 v46, v46, v46
	v_max_f32_e32 v46, v13, v46
	v_sub_f32_e32 v13, v194, v46
	v_exp_f32_e32 v13, v13
	v_sub_f32_e32 v49, v195, v46
	v_exp_f32_e32 v49, v49
	v_sub_f32_e32 v194, v196, v46
	v_exp_f32_e32 v194, v194
	v_sub_f32_e32 v195, v197, v46
	v_exp_f32_e32 v195, v195
	v_sub_f32_e32 v14, v14, v46
	v_add_f32_e32 v48, 0, v13
	v_exp_f32_e32 v14, v14
	v_sub_f32_e32 v188, v188, v46
	v_add_f32_e32 v48, v49, v48
	v_exp_f32_e32 v188, v188
	v_sub_f32_e32 v189, v189, v46
	v_add_f32_e32 v48, v194, v48
	v_exp_f32_e32 v189, v189
	v_sub_f32_e32 v190, v190, v46
	v_add_f32_e32 v48, v195, v48
	v_exp_f32_e32 v190, v190
	v_sub_f32_e32 v191, v191, v46
	v_add_f32_e32 v48, v14, v48
	v_exp_f32_e32 v191, v191
	v_sub_f32_e32 v192, v192, v46
	v_add_f32_e32 v48, v188, v48
	v_exp_f32_e32 v192, v192
	v_sub_f32_e32 v193, v193, v46
	v_add_f32_e32 v48, v189, v48
	v_exp_f32_e32 v193, v193
	v_sub_f32_e32 v196, v198, v46
	v_add_f32_e32 v48, v190, v48
	v_exp_f32_e32 v196, v196
	v_sub_f32_e32 v197, v199, v46
	v_add_f32_e32 v48, v191, v48
	v_exp_f32_e32 v197, v197
	v_sub_f32_e32 v198, v200, v46
	v_add_f32_e32 v48, v192, v48
	v_exp_f32_e32 v198, v198
	v_sub_f32_e32 v199, v201, v46
	v_add_f32_e32 v48, v193, v48
	v_exp_f32_e32 v199, v199
	v_sub_f32_e32 v200, v202, v46
	v_add_f32_e32 v48, v196, v48
	v_exp_f32_e32 v200, v200
	v_sub_f32_e32 v186, v186, v46
	v_add_f32_e32 v48, v197, v48
	v_exp_f32_e32 v207, v186
	v_sub_f32_e32 v186, v187, v46
	v_add_f32_e32 v48, v198, v48
	v_exp_f32_e32 v208, v186
	v_sub_f32_e32 v64, v64, v46
	v_add_f32_e32 v48, v199, v48
	v_exp_f32_e32 v64, v64
	v_sub_f32_e32 v65, v65, v46
	v_add_f32_e32 v48, v200, v48
	v_exp_f32_e32 v65, v65
	v_sub_f32_e32 v62, v62, v46
	v_add_f32_e32 v48, v207, v48
	v_exp_f32_e32 v209, v62
	v_sub_f32_e32 v62, v63, v46
	v_add_f32_e32 v48, v208, v48
	v_exp_f32_e32 v210, v62
	v_sub_f32_e32 v60, v60, v46
	v_add_f32_e32 v48, v64, v48
	v_exp_f32_e32 v211, v60
	v_sub_f32_e32 v60, v61, v46
	v_add_f32_e32 v48, v65, v48
	v_exp_f32_e32 v212, v60
	v_sub_f32_e32 v58, v58, v46
	v_add_f32_e32 v48, v209, v48
	v_exp_f32_e32 v213, v58
	v_sub_f32_e32 v58, v59, v46
	v_add_f32_e32 v48, v210, v48
	v_exp_f32_e32 v214, v58
	v_sub_f32_e32 v56, v56, v46
	v_add_f32_e32 v48, v211, v48
	v_exp_f32_e32 v215, v56
	v_sub_f32_e32 v56, v57, v46
	v_add_f32_e32 v48, v212, v48
	v_exp_f32_e32 v216, v56
	v_sub_f32_e32 v54, v54, v46
	v_add_f32_e32 v48, v213, v48
	v_exp_f32_e32 v217, v54
	v_sub_f32_e32 v54, v55, v46
	v_add_f32_e32 v48, v214, v48
	v_exp_f32_e32 v218, v54
	v_sub_f32_e32 v52, v52, v46
	v_add_f32_e32 v48, v215, v48
	v_exp_f32_e32 v219, v52
	v_sub_f32_e32 v52, v53, v46
	v_add_f32_e32 v48, v216, v48
	v_exp_f32_e32 v220, v52
	v_sub_f32_e32 v50, v50, v46
	v_add_f32_e32 v48, v217, v48
	v_exp_f32_e32 v221, v50
	v_add_f32_e32 v48, v218, v48
	v_add_f32_e32 v48, v219, v48
	v_add_f32_e32 v48, v220, v48
	v_add_f32_e32 v201, v221, v48
	v_sub_f32_e32 v48, v51, v46
	v_exp_f32_e32 v222, v48
	v_sub_f32_e32 v47, v47, v46
	v_cvt_pk_bf16_f32 v48, v13, v49
	v_exp_f32_e32 v13, v47
	v_sub_f32_e32 v12, v12, v46
	v_cvt_pk_bf16_f32 v50, v14, v188
	v_exp_f32_e32 v14, v12
	v_add_f32_e32 v12, v222, v201
	v_add_f32_e32 v12, v13, v12
	v_cvt_pk_bf16_f32 v49, v194, v195
	v_add_f32_e32 v12, v14, v12
	ds_bpermute_b32 v47, v203, v12
	v_cvt_pk_bf16_f32 v51, v189, v190
	ds_read_b64_tr_b16 v[54:55], v179 offset:57600
	ds_read_b64_tr_b16 v[52:53], v179 offset:55296
	ds_read_b64_tr_b16 v[56:57], v179 offset:55328
	ds_read_b64_tr_b16 v[60:61], v179 offset:55360
	ds_read_b64_tr_b16 v[186:187], v179 offset:55392
	ds_read_b64_tr_b16 v[58:59], v179 offset:57632
	ds_read_b64_tr_b16 v[62:63], v179 offset:57664
	ds_read_b64_tr_b16 v[188:189], v179 offset:57696
	v_cvt_pk_bf16_f32 v248, v191, v192
	v_cvt_pk_bf16_f32 v249, v193, v196
	v_cvt_pk_bf16_f32 v250, v197, v198
	v_cvt_pk_bf16_f32 v251, v199, v200
	ds_read_b64_tr_b16 v[234:235], v179 offset:62208
	ds_read_b64_tr_b16 v[232:233], v179 offset:59904
	ds_read_b64_tr_b16 v[236:237], v179 offset:59936
	ds_read_b64_tr_b16 v[240:241], v179 offset:59968
	ds_read_b64_tr_b16 v[244:245], v179 offset:60000
	ds_read_b64_tr_b16 v[238:239], v179 offset:62240
	s_waitcnt lgkmcnt(12)
; __device__ __forceinline__ unsigned cvtpk(float lo, float hi) { const f32v2_t v = {lo, hi}; const bf16v2_t b = __builtin_convertvector(v, bf16v2_t); return __builtin_bit_cast(unsigned, b); }
; __device__ __forceinline__ bf16_t f2bf(float f) { return (bf16_t)cvtpk(f, 0.f); }
; __device__ __forceinline__ v4i16_t lds_tr16(const bf16_t* p) { return __builtin_amdgcn_ds_read_tr16_b64_v4i16((LAS v4i16_t*)p); }
; __device__ void phase_attn(const Params& p, unsigned char* smem, int wave) {
;     ...
; #pragma unroll
;         for (int ks = 0; ks < 5; ++ks) {
;             u32x4 pu; pu.x = cvtpk(sc[2 * ks][0], sc[2 * ks][1]); pu.y = cvtpk(sc[2 * ks][2], sc[2 * ks][3]); pu.z = cvtpk(sc[2 * ks + 1][0], sc[2 * ks + 1][1]); pu.w = cvtpk(sc[2 * ks + 1][2], sc[2 * ks + 1][3]);
;             const bf16x8 pf = __builtin_bit_cast(bf16x8, pu);
;             const bf16_t* vrow = Vs + (16 * w4 + 32 * ks + 4 * gq + (ql >> 2)) * ATT_LD + 4 * (ql & 3);
; #pragma unroll
;             for (int et = 0; et < 4; ++et) {
;                 const v4i16_t t0 = lds_tr16(vrow + 16 * et);
;                 v4i16_t t1 = (v4i16_t){0, 0, 0, 0};
;                 if (ks < 4) t1 = lds_tr16(vrow + 16 * ATT_LD + 16 * et);
;                 const bf16x8 vf = __builtin_shufflevector(t0, t1, 0, 1, 2, 3, 4, 5, 6, 7);
;                 oacc[et] = __builtin_amdgcn_mfma_f32_16x16x32_bf16(pf, vf, oacc[et], 0, 0, 0); }
;             __builtin_amdgcn_sched_barrier(0);
;         }
; #pragma unroll
;         for (int j = 0; j < 4; ++j) { const float dq = __shfl(den, 4 * gq + j); const float inv = __builtin_amdgcn_rcpf(dq);
;             const int tok = gbase + (i0 + 16 * w4 + 4 * gq + j) * d + res;
; #pragma unroll
;             for (int et = 0; et < 4; ++et) ato[(size_t)tok * 512 + h * 64 + 16 * et + ql] = f2bf(oacc[et][j] * inv); }
	v_mfma_f32_16x16x32_bf16 v[52:55], v[48:51], v[52:55], 0
	ds_read_b64_tr_b16 v[242:243], v179 offset:62272
	ds_read_b64_tr_b16 v[246:247], v179 offset:62304
	v_add_f32_e32 v47, v12, v47
	ds_bpermute_b32 v223, v204, v47
	s_waitcnt lgkmcnt(11)
	v_mfma_f32_16x16x32_bf16 v[56:59], v[48:51], v[56:59], 0
	s_waitcnt lgkmcnt(10)
	v_mfma_f32_16x16x32_bf16 v[60:63], v[48:51], v[60:63], 0
	s_waitcnt lgkmcnt(9)
	v_mfma_f32_16x16x32_bf16 v[48:51], v[48:51], v[186:189], 0
	v_cvt_pk_bf16_f32 v186, v207, v208
	v_cvt_pk_bf16_f32 v187, v64, v65
	v_cvt_pk_bf16_f32 v188, v209, v210
	v_cvt_pk_bf16_f32 v189, v211, v212
	ds_read_b64_tr_b16 v[192:193], v180 offset:11520
	ds_read_b64_tr_b16 v[190:191], v179 offset:64512
	ds_read_b64_tr_b16 v[194:195], v179 offset:64544
	ds_read_b64_tr_b16 v[198:199], v179 offset:64576
	ds_read_b64_tr_b16 v[202:203], v179 offset:64608
	ds_read_b64_tr_b16 v[196:197], v180 offset:11552
	s_waitcnt lgkmcnt(13)
	v_mfma_f32_16x16x32_bf16 v[52:55], v[248:251], v[232:235], v[52:55]
	ds_read_b64_tr_b16 v[200:201], v180 offset:11584
	ds_read_b64_tr_b16 v[204:205], v180 offset:11616
	s_waitcnt lgkmcnt(11)
	v_mfma_f32_16x16x32_bf16 v[56:59], v[248:251], v[236:239], v[56:59]
	s_waitcnt lgkmcnt(10)
	v_mfma_f32_16x16x32_bf16 v[60:63], v[248:251], v[240:243], v[60:63]
	s_waitcnt lgkmcnt(9)
	v_mfma_f32_16x16x32_bf16 v[48:51], v[248:251], v[244:247], v[48:51]
	v_cvt_pk_bf16_f32 v248, v213, v214
	v_cvt_pk_bf16_f32 v249, v215, v216
	v_cvt_pk_bf16_f32 v250, v217, v218
	v_cvt_pk_bf16_f32 v251, v219, v220
	ds_read_b64_tr_b16 v[234:235], v180 offset:16128
	ds_read_b64_tr_b16 v[232:233], v180 offset:13824
	ds_read_b64_tr_b16 v[236:237], v180 offset:13856
	ds_read_b64_tr_b16 v[240:241], v180 offset:13888
	ds_read_b64_tr_b16 v[244:245], v180 offset:13920
	ds_read_b64_tr_b16 v[238:239], v180 offset:16160
	s_waitcnt lgkmcnt(12)
	v_mfma_f32_16x16x32_bf16 v[52:55], v[186:189], v[190:193], v[52:55]
	ds_read_b64_tr_b16 v[242:243], v180 offset:16192
	ds_read_b64_tr_b16 v[246:247], v180 offset:16224
	s_waitcnt lgkmcnt(10)
	v_mfma_f32_16x16x32_bf16 v[56:59], v[186:189], v[194:197], v[56:59]
	s_waitcnt lgkmcnt(9)
	v_mfma_f32_16x16x32_bf16 v[60:63], v[186:189], v[198:201], v[60:63]
	s_waitcnt lgkmcnt(8)
	v_mfma_f32_16x16x32_bf16 v[48:51], v[186:189], v[202:205], v[48:51]
	v_cvt_pk_bf16_f32 v12, v221, v222
	v_cvt_pk_bf16_f32 v13, v13, v14
	v_mov_b32_e32 v14, v15
	ds_read_b64_tr_b16 v[186:187], v180 offset:18432
	ds_read_b64_tr_b16 v[190:191], v180 offset:18464
	ds_read_b64_tr_b16 v[194:195], v180 offset:18496
	ds_read_b64_tr_b16 v[198:199], v180 offset:18528
	v_mov_b32_e32 v188, v15
	v_mov_b32_e32 v189, v15
	v_mov_b32_e32 v192, v15
	v_mov_b32_e32 v193, v15
	v_mov_b32_e32 v196, v15
	v_mov_b32_e32 v197, v15
	v_mov_b32_e32 v200, v15
	v_mov_b32_e32 v201, v15
	s_waitcnt lgkmcnt(10)
	v_mfma_f32_16x16x32_bf16 v[52:55], v[248:251], v[232:235], v[52:55]
	s_waitcnt lgkmcnt(6)
	v_mfma_f32_16x16x32_bf16 v[56:59], v[248:251], v[236:239], v[56:59]
	s_waitcnt lgkmcnt(5)
	v_mfma_f32_16x16x32_bf16 v[60:63], v[248:251], v[240:243], v[60:63]
	s_waitcnt lgkmcnt(4)
	v_mfma_f32_16x16x32_bf16 v[48:51], v[248:251], v[244:247], v[48:51]
	s_waitcnt lgkmcnt(3)
	v_mfma_f32_16x16x32_bf16 v[52:55], v[12:15], v[186:189], v[52:55]
	s_waitcnt lgkmcnt(2)
	v_mfma_f32_16x16x32_bf16 v[56:59], v[12:15], v[190:193], v[56:59]
	s_waitcnt lgkmcnt(1)
	v_mfma_f32_16x16x32_bf16 v[60:63], v[12:15], v[194:197], v[60:63]
	s_waitcnt lgkmcnt(0)
	v_mfma_f32_16x16x32_bf16 v[48:51], v[12:15], v[198:201], v[48:51]
	v_or_b32_e32 v14, v206, v141
	v_add_f32_e32 v12, v47, v223
	v_lshlrev_b32_e32 v14, 2, v14
	ds_bpermute_b32 v47, v14, v12
	s_add_i32 s62, s62, s61
	s_lshl_b32 s18, s57, 7
	s_add_u32 s18, s59, s18
	v_or_b32_e32 v13, v139, v141
	s_addc_u32 s19, s60, 0
	v_mov_b32_e32 v139, v15
	s_waitcnt lgkmcnt(0)
	v_rcp_f32_e32 v47, v47
	v_lshl_add_u64 v[64:65], s[18:19], 0, v[138:139]
	v_lshlrev_b32_e32 v139, s58, v13
	v_add_u32_e32 v186, s62, v139
	v_ashrrev_i32_e32 v187, 31, v186
	v_lshlrev_b64 v[186:187], 10, v[186:187]
	v_mul_f32_e32 v52, v52, v47
	v_lshl_add_u64 v[186:187], v[64:65], 0, v[186:187]
	v_cvt_pk_bf16_f32 v52, v52, s0
	global_store_short v[186:187], v52, off
	v_mul_f32_e32 v52, v56, v47
	ds_bpermute_b32 v56, v14, v12 offset:4
	v_cvt_pk_bf16_f32 v52, v52, s0
	global_store_short v[186:187], v52, off offset:32
	v_mul_f32_e32 v52, v60, v47
	v_mul_f32_e32 v47, v48, v47
	v_cvt_pk_bf16_f32 v47, v47, s0
	global_store_short v[186:187], v47, off offset:96
	s_waitcnt lgkmcnt(0)
	v_rcp_f32_e32 v47, v56
	v_or_b32_e32 v48, 1, v13
	v_cvt_pk_bf16_f32 v52, v52, s0
	v_lshlrev_b32_e32 v48, s58, v48
	global_store_short v[186:187], v52, off offset:64
	v_add_u32_e32 v186, s62, v48
	v_ashrrev_i32_e32 v187, 31, v186
	v_lshlrev_b64 v[186:187], 10, v[186:187]
	v_mul_f32_e32 v48, v53, v47
	v_lshl_add_u64 v[186:187], v[64:65], 0, v[186:187]
	v_cvt_pk_bf16_f32 v48, v48, s0
	ds_bpermute_b32 v52, v14, v12 offset:8
	global_store_short v[186:187], v48, off
	v_mul_f32_e32 v48, v57, v47
	v_cvt_pk_bf16_f32 v48, v48, s0
	global_store_short v[186:187], v48, off offset:32
	v_mul_f32_e32 v48, v61, v47
	v_mul_f32_e32 v47, v49, v47
	v_cvt_pk_bf16_f32 v48, v48, s0
	v_cvt_pk_bf16_f32 v47, v47, s0
	global_store_short v[186:187], v48, off offset:64
	global_store_short v[186:187], v47, off offset:96
	s_waitcnt lgkmcnt(0)
	v_rcp_f32_e32 v47, v52
	v_or_b32_e32 v48, 2, v13
	v_lshlrev_b32_e32 v48, s58, v48
	v_add_u32_e32 v48, s62, v48
	v_or_b32_e32 v14, 12, v14
	v_ashrrev_i32_e32 v49, 31, v48
	ds_bpermute_b32 v14, v14, v12
	v_lshlrev_b64 v[48:49], 10, v[48:49]
	v_mul_f32_e32 v52, v54, v47
	v_lshl_add_u64 v[48:49], v[64:65], 0, v[48:49]
	v_cvt_pk_bf16_f32 v52, v52, s0
	global_store_short v[48:49], v52, off
	v_mul_f32_e32 v52, v58, v47
	v_cvt_pk_bf16_f32 v52, v52, s0
	global_store_short v[48:49], v52, off offset:32
	v_mul_f32_e32 v52, v62, v47
	v_mul_f32_e32 v47, v50, v47
	s_waitcnt lgkmcnt(0)
	v_rcp_f32_e32 v14, v14
	v_or_b32_e32 v13, 3, v13
	v_cvt_pk_bf16_f32 v52, v52, s0
	v_cvt_pk_bf16_f32 v47, v47, s0
	v_lshlrev_b32_e32 v13, s58, v13
	global_store_short v[48:49], v52, off offset:64
	global_store_short v[48:49], v47, off offset:96
	v_add_u32_e32 v48, s62, v13
	v_ashrrev_i32_e32 v49, 31, v48
	v_lshlrev_b64 v[48:49], 10, v[48:49]
	v_mul_f32_e32 v13, v55, v14
	v_lshl_add_u64 v[48:49], v[64:65], 0, v[48:49]
	v_cvt_pk_bf16_f32 v13, v13, s0
	global_store_short v[48:49], v13, off
	v_mul_f32_e32 v13, v59, v14
	v_cvt_pk_bf16_f32 v13, v13, s0
	global_store_short v[48:49], v13, off offset:32
	v_mul_f32_e32 v13, v63, v14
	v_cvt_pk_bf16_f32 v13, v13, s0
	global_store_short v[48:49], v13, off offset:64
	v_mul_f32_e32 v13, v51, v14
	v_cvt_pk_bf16_f32 v13, v13, s0
	global_store_short v[48:49], v13, off offset:96
	s_and_saveexec_b64 s[20:21], s[0:1]
	s_cbranch_execz .LBB0_719
; __device__ void phase_attn(const Params& p, unsigned char* smem, int wave) {
;     ...
;         if (gq == 0) { const int tok = gbase + qi * d + res; lse[((size_t)br * NTOK + tok) * 8 + h] = mx * 0.6931471805599453f + __logf(den); }
	v_cmp_gt_f32_e32 vcc, s53, v12
	s_nop 1
	v_cndmask_b32_e64 v13, 0, 32, vcc
	v_ldexp_f32 v12, v12, v13
	v_log_f32_e32 v13, v12
	v_lshlrev_b32_e32 v12, s58, v45
	v_add_u32_e32 v12, s62, v12
	v_mul_f32_e32 v14, 0x3f317217, v13
	v_fma_f32 v14, v13, s54, -v14
	v_fmac_f32_e32 v14, 0x3377d1cf, v13
	v_fmac_f32_e32 v14, 0x3f317217, v13
	v_cmp_lt_f32_e64 s[18:19], |v13|, s55
	s_nop 1
	v_cndmask_b32_e64 v13, v13, v14, s[18:19]
	v_cndmask_b32_e32 v14, 0, v184, vcc
	v_sub_f32_e32 v14, v13, v14
	v_ashrrev_i32_e32 v13, 31, v12
	v_mad_i64_i32 v[12:13], s[18:19], s42, v185, v[12:13]
	v_lshlrev_b64 v[12:13], 5, v[12:13]
	v_lshl_add_u64 v[12:13], s[40:41], 0, v[12:13]
	s_lshl_b32 s42, s57, 2
	v_fmac_f32_e32 v14, 0x3f317218, v46
	v_lshl_add_u64 v[12:13], v[12:13], 0, s[42:43]
	global_store_dword v[12:13], v14, off
	s_branch .LBB0_719
